# S5 scan phases: workgroups of one XCD take the four channel groups that share the 128-byte lines of u and y (XCD-aware task mapping)
# speedup vs baseline: 1.0330x; 1.0128x over previous
; __device__ __forceinline__ bf16x8 pack8(const float (&f)[8]) { u32x4 h; h.x = pk2(f[0], f[1]); h.y = pk2(f[2], f[3]); h.z = pk2(f[4], f[5]); h.w = pk2(f[6], f[7]); return __builtin_bit_cast(bf16x8, h); }
;     __device__ __forceinline__ bf16* R(int i) const { return (bf16*)(ws + OFF_R0 + (size_t)i * RSZ); }
; template <bool FINAL> __device__ __forceinline__ void phase_s5_scan(const Fr& F) {
;     const bf16* U = F.R(1); float* E = (float*)F.R(6);
;     float* BUl = (float*)(F.lds + F.wave * 16384);
;     const int lane = F.lane, l15 = lane & 15, lq = lane >> 4;
;     const float* BBf = (const float*)(F.ws + OFF_BB);
;     const int sg = F.gw >> 4, g = sg & 63, s = sg >> 6;
;     const f32x4 av = *(const f32x4*)((const float*)(F.ws + OFF_S5A) + (sg * 64 + lane) * 4);
;     const float ar = av.x, ai = av.y;
;     bf16x8 B1[8];
; #pragma unroll
;     for (int nt = 0; nt < 8; ++nt) {
;         const int n = 16 * nt + l15; const float* bp = BBf + (size_t)(sg * 64 + (n & 63)) * 32 + 16 * (n >> 6) + 8 * (lq & 1);
;         const f32x4 t0 = *(const f32x4*)bp, t1 = *(const f32x4*)(bp + 4); const float f[8] = {t0.x, t0.y, t0.z, t0.w, t1.x, t1.y, t1.z, t1.w};
;         B1[nt] = lq < 2 ? pack8(f) : (bf16x8){0, 0, 0, 0, 0, 0, 0, 0};
;     }
;     bf16x8 Chi[4];
;     if (FINAL) {
; #pragma unroll
;         for (int ks = 0; ks < 4; ++ks) {
;             const int k = 32 * ks + 8 * lq; const float* cp = (k < 64 ? F.a->in[32] : F.a->in[33]) + (size_t)g * 1024 + l15 * 64 + (k & 63); const float sg_ = k < 64 ? 1.f : -1.f;
;             const f32x4 t0 = *(const f32x4*)cp, t1 = *(const f32x4*)(cp + 4); const float f[8] = {sg_ * t0.x, sg_ * t0.y, sg_ * t0.z, sg_ * t0.w, sg_ * t1.x, sg_ * t1.y, sg_ * t1.z, sg_ * t1.w};
;             Chi[ks] = pack8(f);
;         }
;     }
;     u32x4 ua[4]; float e0 = 0.f, e1 = 0.f;
;     {   const int ti = F.gw & 15, b = ti / 68, chunk = ti - b * 68;
; #pragma unroll
;         for (int sb = 0; sb < 4; ++sb) ua[sb] = lq < 2 ? *(const u32x4*)(U + ((size_t)b * TB + tokof(s, chunk * 64 + sb * 16 + l15)) * D + g * 16 + 8 * lq) : (u32x4){0u, 0u, 0u, 0u};
.LBB0_1558:
	s_cmp_lt_i32 s34, 16
	s_cselect_b64 s[10:11], -1, 0
	s_cmp_gt_i32 s35, 15
	s_cselect_b64 s[6:7], -1, 0
	s_and_b64 s[6:7], s[10:11], s[6:7]
	s_andn2_b64 vcc, exec, s[6:7]
	v_cmp_gt_u32_e64 s[6:7], 32, v130
	s_cbranch_vccnz .LBB0_1604
	s_and_b32 s15, s2, 7
	s_lshr_b32 s16, s2, 3
	s_lshr_b32 s17, s16, 3
	s_lshl_b32 s15, s15, 2
	s_add_i32 s15, s15, s17
	s_lshr_b32 s9, s15, 4
	s_and_b32 s15, s15, 15
	s_and_b32 s16, s16, 7
	s_lshr_b32 s17, s16, 1
	s_lshl_b32 s8, s15, 2
	s_add_i32 s8, s8, s17
	s_lshl_b32 s3, s9, 6
	s_add_i32 s3, s3, s8
	s_and_b32 s16, s16, 1
	s_lshl_b32 s55, s16, 3
	s_add_i32 s55, s55, s68
	s_cmp_lt_u32 s55, 4
	s_cselect_b32 s56, 5, 4
	v_and_b32_e32 v236, 15, v130
	v_lshrrev_b32_e32 v237, 4, v130
	s_add_u32 s42, s26, 0x100000
	s_addc_u32 s43, s27, 0
	s_add_u32 s44, s26, 0x40000
	s_addc_u32 s45, s27, 0
	s_add_u32 s20, s26, 0x3400000
	s_addc_u32 s21, s27, 0
	s_add_u32 s22, s26, 0xde00000
	s_addc_u32 s23, s27, 0
	s_lshl_b32 s15, s3, 6
	v_add_u32_e32 v216, s15, v236
	v_and_b32_e32 v217, 1, v237
	v_lshlrev_b32_e32 v217, 5, v217
	v_lshl_add_u32 v218, v216, 7, v217
	v_add_u32_e32 v219, 0x1000, v218
	global_load_dwordx4 v[56:59], v218, s[42:43] offset:0
	global_load_dwordx4 v[60:63], v218, s[42:43] offset:16
	global_load_dwordx4 v[64:67], v218, s[42:43] offset:2048
	global_load_dwordx4 v[68:71], v218, s[42:43] offset:2064
	global_load_dwordx4 v[72:75], v219, s[42:43] offset:0
	global_load_dwordx4 v[76:79], v219, s[42:43] offset:16
	global_load_dwordx4 v[80:83], v219, s[42:43] offset:2048
	global_load_dwordx4 v[84:87], v219, s[42:43] offset:2064
	global_load_dwordx4 v[88:91], v218, s[42:43] offset:64
	global_load_dwordx4 v[92:95], v218, s[42:43] offset:80
	global_load_dwordx4 v[96:99], v218, s[42:43] offset:2112
	global_load_dwordx4 v[100:103], v218, s[42:43] offset:2128
	global_load_dwordx4 v[104:107], v219, s[42:43] offset:64
	global_load_dwordx4 v[108:111], v219, s[42:43] offset:80
	global_load_dwordx4 v[112:115], v219, s[42:43] offset:2112
	global_load_dwordx4 v[116:119], v219, s[42:43] offset:2128
	v_lshlrev_b32_e32 v220, 4, v216
	global_load_dwordx2 v[32:33], v220, s[44:45] offset:0
	global_load_dwordx2 v[34:35], v220, s[44:45] offset:256
	global_load_dwordx2 v[36:37], v220, s[44:45] offset:512
	global_load_dwordx2 v[38:39], v220, s[44:45] offset:768
	s_waitcnt vmcnt(0)
	v_cmp_gt_u32_e32 vcc, 2, v237
	v_cvt_pk_bf16_f32 v0, v56, v57
	v_cvt_pk_bf16_f32 v1, v58, v59
	v_cvt_pk_bf16_f32 v2, v60, v61
	v_cvt_pk_bf16_f32 v3, v62, v63
	v_cvt_pk_bf16_f32 v4, v64, v65
	v_cvt_pk_bf16_f32 v5, v66, v67
	v_cvt_pk_bf16_f32 v6, v68, v69
	v_cvt_pk_bf16_f32 v7, v70, v71
	v_cvt_pk_bf16_f32 v8, v72, v73
	v_cvt_pk_bf16_f32 v9, v74, v75
	v_cvt_pk_bf16_f32 v10, v76, v77
	v_cvt_pk_bf16_f32 v11, v78, v79
	v_cvt_pk_bf16_f32 v12, v80, v81
	v_cvt_pk_bf16_f32 v13, v82, v83
	v_cvt_pk_bf16_f32 v14, v84, v85
	v_cvt_pk_bf16_f32 v15, v86, v87
	v_cvt_pk_bf16_f32 v16, v88, v89
	v_cvt_pk_bf16_f32 v17, v90, v91
	v_cvt_pk_bf16_f32 v18, v92, v93
	v_cvt_pk_bf16_f32 v19, v94, v95
	v_cvt_pk_bf16_f32 v20, v96, v97
	v_cvt_pk_bf16_f32 v21, v98, v99
	v_cvt_pk_bf16_f32 v22, v100, v101
	v_cvt_pk_bf16_f32 v23, v102, v103
	v_cvt_pk_bf16_f32 v24, v104, v105
	v_cvt_pk_bf16_f32 v25, v106, v107
	v_cvt_pk_bf16_f32 v26, v108, v109
	v_cvt_pk_bf16_f32 v27, v110, v111
	v_cvt_pk_bf16_f32 v28, v112, v113
	v_cvt_pk_bf16_f32 v29, v114, v115
	v_cvt_pk_bf16_f32 v30, v116, v117
	v_cvt_pk_bf16_f32 v31, v118, v119
	v_cndmask_b32_e32 v0, 0, v0, vcc
	v_cndmask_b32_e32 v1, 0, v1, vcc
	v_cndmask_b32_e32 v2, 0, v2, vcc
	v_cndmask_b32_e32 v3, 0, v3, vcc
	v_cndmask_b32_e32 v4, 0, v4, vcc
	v_cndmask_b32_e32 v5, 0, v5, vcc
	v_cndmask_b32_e32 v6, 0, v6, vcc
	v_cndmask_b32_e32 v7, 0, v7, vcc
	v_cndmask_b32_e32 v8, 0, v8, vcc
	v_cndmask_b32_e32 v9, 0, v9, vcc
	v_cndmask_b32_e32 v10, 0, v10, vcc
	v_cndmask_b32_e32 v11, 0, v11, vcc
	v_cndmask_b32_e32 v12, 0, v12, vcc
	v_cndmask_b32_e32 v13, 0, v13, vcc
	v_cndmask_b32_e32 v14, 0, v14, vcc
	v_cndmask_b32_e32 v15, 0, v15, vcc
	v_cndmask_b32_e32 v16, 0, v16, vcc
	v_cndmask_b32_e32 v17, 0, v17, vcc
	v_cndmask_b32_e32 v18, 0, v18, vcc
	v_cndmask_b32_e32 v19, 0, v19, vcc
	v_cndmask_b32_e32 v20, 0, v20, vcc
	v_cndmask_b32_e32 v21, 0, v21, vcc
	v_cndmask_b32_e32 v22, 0, v22, vcc
	v_cndmask_b32_e32 v23, 0, v23, vcc
	v_cndmask_b32_e32 v24, 0, v24, vcc
	v_cndmask_b32_e32 v25, 0, v25, vcc
	v_cndmask_b32_e32 v26, 0, v26, vcc
	v_cndmask_b32_e32 v27, 0, v27, vcc
	v_cndmask_b32_e32 v28, 0, v28, vcc
	v_cndmask_b32_e32 v29, 0, v29, vcc
	v_cndmask_b32_e32 v30, 0, v30, vcc
	v_cndmask_b32_e32 v31, 0, v31, vcc
	s_cmp_eq_u32 s9, 0
	s_mov_b32 s18, 0xffffe000
	s_cselect_b32 s18, 0x2000, s18
	v_mov_b32_e32 v243, s18
	s_mov_b32 s14, s55
	s_lshl_b32 s15, s14, 2
	v_lshrrev_b32_e32 v244, 2, v236
	v_add_u32_e32 v244, s15, v244
	v_mul_u32_u24_e32 v245, 0xf1, v244
	v_lshrrev_b32_e32 v245, 14, v245
	v_mul_u32_u24_e32 v232, 68, v245
	v_sub_u32_e32 v244, v244, v232
	v_and_b32_e32 v232, 3, v236
	v_lshl_add_u32 v232, v244, 6, v232
	v_mov_b32_e32 v233, 0x11ff
	v_mov_b32_e32 v234, 0xff
	v_cmp_gt_u32_e32 vcc, 4, v244
	s_nop 1
	v_cndmask_b32_e32 v233, v233, v234, vcc
	v_sub_u32_e32 v233, v233, v232
	s_cmp_eq_u32 s9, 0
	s_cselect_b64 vcc, -1, 0
	s_nop 1
	v_cndmask_b32_e32 v232, v233, v232, vcc
	v_mul_u32_u24_e32 v245, 0x1100, v245
	v_add_u32_e32 v232, v232, v245
	s_lshl_b32 s16, s8, 5
	v_and_b32_e32 v233, 1, v237
	v_lshl_add_u32 v233, v233, 4, s16
	v_lshl_add_u32 v238, v232, 11, v233
	global_load_dwordx4 v[56:59], v238, s[20:21]
	v_add_u32_e32 v238, v238, v243
	global_load_dwordx4 v[60:63], v238, s[20:21]
	v_add_u32_e32 v238, v238, v243
	global_load_dwordx4 v[64:67], v238, s[20:21]
	v_add_u32_e32 v238, v238, v243
	global_load_dwordx4 v[68:71], v238, s[20:21]
	v_add_u32_e32 v238, v238, v243
	global_load_dwordx4 v[72:75], v238, s[20:21]
	v_add_u32_e32 v238, v238, v243
	global_load_dwordx4 v[76:79], v238, s[20:21]
	v_add_u32_e32 v238, v238, v243
	global_load_dwordx4 v[80:83], v238, s[20:21]
	v_add_u32_e32 v238, v238, v243
	global_load_dwordx4 v[84:87], v238, s[20:21]
	v_add_u32_e32 v238, v238, v243
	global_load_dwordx4 v[88:91], v238, s[20:21]
	v_add_u32_e32 v238, v238, v243
	global_load_dwordx4 v[92:95], v238, s[20:21]
	v_add_u32_e32 v238, v238, v243
	global_load_dwordx4 v[96:99], v238, s[20:21]
	v_add_u32_e32 v238, v238, v243
	global_load_dwordx4 v[100:103], v238, s[20:21]
	v_add_u32_e32 v238, v238, v243
	global_load_dwordx4 v[104:107], v238, s[20:21]
	v_add_u32_e32 v238, v238, v243
	global_load_dwordx4 v[108:111], v238, s[20:21]
	v_add_u32_e32 v238, v238, v243
	global_load_dwordx4 v[112:115], v238, s[20:21]
	v_add_u32_e32 v238, v238, v243
	global_load_dwordx4 v[116:119], v238, s[20:21]
	v_add_u32_e32 v238, v238, v243
	s_mov_b32 s19, 0
	s_waitcnt vmcnt(0)

; __device__ __forceinline__ bf16x8 pack8(const float (&f)[8]) { u32x4 h; h.x = pk2(f[0], f[1]); h.y = pk2(f[2], f[3]); h.z = pk2(f[4], f[5]); h.w = pk2(f[6], f[7]); return __builtin_bit_cast(bf16x8, h); }
;     __device__ __forceinline__ bf16* R(int i) const { return (bf16*)(ws + OFF_R0 + (size_t)i * RSZ); }
; template <bool FINAL> __device__ __forceinline__ void phase_s5_scan(const Fr& F) {
;     const bf16* U = F.R(1); float* E = (float*)F.R(6);
;     float* BUl = (float*)(F.lds + F.wave * 16384);
;     const int lane = F.lane, l15 = lane & 15, lq = lane >> 4;
;     const float* BBf = (const float*)(F.ws + OFF_BB);
;     const int sg = F.gw >> 4, g = sg & 63, s = sg >> 6;
;     const f32x4 av = *(const f32x4*)((const float*)(F.ws + OFF_S5A) + (sg * 64 + lane) * 4);
;     const float ar = av.x, ai = av.y;
;     bf16x8 B1[8];
; #pragma unroll
;     for (int nt = 0; nt < 8; ++nt) {
;         const int n = 16 * nt + l15; const float* bp = BBf + (size_t)(sg * 64 + (n & 63)) * 32 + 16 * (n >> 6) + 8 * (lq & 1);
;         const f32x4 t0 = *(const f32x4*)bp, t1 = *(const f32x4*)(bp + 4); const float f[8] = {t0.x, t0.y, t0.z, t0.w, t1.x, t1.y, t1.z, t1.w};
;         B1[nt] = lq < 2 ? pack8(f) : (bf16x8){0, 0, 0, 0, 0, 0, 0, 0};
;     }
;     bf16x8 Chi[4];
;     if (FINAL) {
; #pragma unroll
;         for (int ks = 0; ks < 4; ++ks) {
;             const int k = 32 * ks + 8 * lq; const float* cp = (k < 64 ? F.a->in[32] : F.a->in[33]) + (size_t)g * 1024 + l15 * 64 + (k & 63); const float sg_ = k < 64 ? 1.f : -1.f;
;             const f32x4 t0 = *(const f32x4*)cp, t1 = *(const f32x4*)(cp + 4); const float f[8] = {sg_ * t0.x, sg_ * t0.y, sg_ * t0.z, sg_ * t0.w, sg_ * t1.x, sg_ * t1.y, sg_ * t1.z, sg_ * t1.w};
;             Chi[ks] = pack8(f);
;         }
;     }
;     u32x4 ua[4]; float e0 = 0.f, e1 = 0.f;
;     {   const int ti = F.gw & 15, b = ti / 68, chunk = ti - b * 68;
; #pragma unroll
;         for (int sb = 0; sb < 4; ++sb) ua[sb] = lq < 2 ? *(const u32x4*)(U + ((size_t)b * TB + tokof(s, chunk * 64 + sb * 16 + l15)) * D + g * 16 + 8 * lq) : (u32x4){0u, 0u, 0u, 0u};
;         if (FINAL) { const float* e = E + ((size_t)(((s * 4 + b) * 64 + g) * 68 + chunk) * 64 + lane) * 2; e0 = e[0]; e1 = e[1]; } }
.LBB0_1716:
	s_or_b64 exec, exec, s[6:7]
	v_cmp_gt_i32_e32 vcc, 18, v2
	v_cmp_lt_i32_e64 s[6:7], 17, v3
	s_and_b64 s[6:7], vcc, s[6:7]
	s_and_saveexec_b64 s[12:13], s[6:7]
	s_cbranch_execz .LBB0_1762
	s_and_b32 s15, s2, 7
	s_lshr_b32 s16, s2, 3
	s_lshr_b32 s17, s16, 3
	s_lshl_b32 s15, s15, 2
	s_add_i32 s15, s15, s17
	s_lshr_b32 s9, s15, 4
	s_and_b32 s15, s15, 15
	s_and_b32 s16, s16, 7
	s_lshr_b32 s17, s16, 1
	s_lshl_b32 s8, s15, 2
	s_add_i32 s8, s8, s17
	s_lshl_b32 s3, s9, 6
	s_add_i32 s3, s3, s8
	s_and_b32 s16, s16, 1
	s_lshl_b32 s55, s16, 3
	s_add_i32 s55, s55, s68
	s_cmp_lt_u32 s55, 4
	s_cselect_b32 s56, 5, 4
	v_and_b32_e32 v236, 15, v130
	v_lshrrev_b32_e32 v237, 4, v130
	s_add_u32 s42, s26, 0x100000
	s_addc_u32 s43, s27, 0
	s_add_u32 s44, s26, 0x40000
	s_addc_u32 s45, s27, 0
	s_add_u32 s20, s26, 0x3400000
	s_addc_u32 s21, s27, 0
	s_add_u32 s22, s26, 0xde00000
	s_addc_u32 s23, s27, 0
	s_mul_i32 s15, s9, 0x2200000
	s_add_u32 s24, s26, s15
	s_addc_u32 s25, s27, 0
	s_add_u32 s24, s24, 0x9a00000
	s_addc_u32 s25, s25, 0
	s_load_dwordx2 s[46:47], s[0:1], 0x100
	s_load_dwordx2 s[48:49], s[0:1], 0x108
	s_lshl_b32 s15, s3, 6
	v_add_u32_e32 v216, s15, v236
	v_and_b32_e32 v217, 1, v237
	v_lshlrev_b32_e32 v217, 5, v217
	v_lshl_add_u32 v218, v216, 7, v217
	v_add_u32_e32 v219, 0x1000, v218
	global_load_dwordx4 v[56:59], v218, s[42:43] offset:0
	global_load_dwordx4 v[60:63], v218, s[42:43] offset:16
	global_load_dwordx4 v[64:67], v218, s[42:43] offset:2048
	global_load_dwordx4 v[68:71], v218, s[42:43] offset:2064
	global_load_dwordx4 v[72:75], v219, s[42:43] offset:0
	global_load_dwordx4 v[76:79], v219, s[42:43] offset:16
	global_load_dwordx4 v[80:83], v219, s[42:43] offset:2048
	global_load_dwordx4 v[84:87], v219, s[42:43] offset:2064
	global_load_dwordx4 v[88:91], v218, s[42:43] offset:64
	global_load_dwordx4 v[92:95], v218, s[42:43] offset:80
	global_load_dwordx4 v[96:99], v218, s[42:43] offset:2112
	global_load_dwordx4 v[100:103], v218, s[42:43] offset:2128
	global_load_dwordx4 v[104:107], v219, s[42:43] offset:64
	global_load_dwordx4 v[108:111], v219, s[42:43] offset:80
	global_load_dwordx4 v[112:115], v219, s[42:43] offset:2112
	global_load_dwordx4 v[116:119], v219, s[42:43] offset:2128
	v_lshlrev_b32_e32 v220, 4, v216
	global_load_dwordx2 v[32:33], v220, s[44:45] offset:0
	global_load_dwordx2 v[34:35], v220, s[44:45] offset:256
	global_load_dwordx2 v[36:37], v220, s[44:45] offset:512
	global_load_dwordx2 v[38:39], v220, s[44:45] offset:768
	s_waitcnt vmcnt(0)
	v_cmp_gt_u32_e32 vcc, 2, v237
	v_cvt_pk_bf16_f32 v0, v56, v57
	v_cvt_pk_bf16_f32 v1, v58, v59
	v_cvt_pk_bf16_f32 v2, v60, v61
	v_cvt_pk_bf16_f32 v3, v62, v63
	v_cvt_pk_bf16_f32 v4, v64, v65
	v_cvt_pk_bf16_f32 v5, v66, v67
	v_cvt_pk_bf16_f32 v6, v68, v69
	v_cvt_pk_bf16_f32 v7, v70, v71
	v_cvt_pk_bf16_f32 v8, v72, v73
	v_cvt_pk_bf16_f32 v9, v74, v75
	v_cvt_pk_bf16_f32 v10, v76, v77
	v_cvt_pk_bf16_f32 v11, v78, v79
	v_cvt_pk_bf16_f32 v12, v80, v81
	v_cvt_pk_bf16_f32 v13, v82, v83
	v_cvt_pk_bf16_f32 v14, v84, v85
	v_cvt_pk_bf16_f32 v15, v86, v87
	v_cvt_pk_bf16_f32 v16, v88, v89
	v_cvt_pk_bf16_f32 v17, v90, v91
	v_cvt_pk_bf16_f32 v18, v92, v93
	v_cvt_pk_bf16_f32 v19, v94, v95
	v_cvt_pk_bf16_f32 v20, v96, v97
	v_cvt_pk_bf16_f32 v21, v98, v99
	v_cvt_pk_bf16_f32 v22, v100, v101
	v_cvt_pk_bf16_f32 v23, v102, v103
	v_cvt_pk_bf16_f32 v24, v104, v105
	v_cvt_pk_bf16_f32 v25, v106, v107
	v_cvt_pk_bf16_f32 v26, v108, v109
	v_cvt_pk_bf16_f32 v27, v110, v111
	v_cvt_pk_bf16_f32 v28, v112, v113
	v_cvt_pk_bf16_f32 v29, v114, v115
	v_cvt_pk_bf16_f32 v30, v116, v117
	v_cvt_pk_bf16_f32 v31, v118, v119
	v_cndmask_b32_e32 v0, 0, v0, vcc
	v_cndmask_b32_e32 v1, 0, v1, vcc
	v_cndmask_b32_e32 v2, 0, v2, vcc
	v_cndmask_b32_e32 v3, 0, v3, vcc
	v_cndmask_b32_e32 v4, 0, v4, vcc
	v_cndmask_b32_e32 v5, 0, v5, vcc
	v_cndmask_b32_e32 v6, 0, v6, vcc
	v_cndmask_b32_e32 v7, 0, v7, vcc
	v_cndmask_b32_e32 v8, 0, v8, vcc
	v_cndmask_b32_e32 v9, 0, v9, vcc
	v_cndmask_b32_e32 v10, 0, v10, vcc
	v_cndmask_b32_e32 v11, 0, v11, vcc
	v_cndmask_b32_e32 v12, 0, v12, vcc
	v_cndmask_b32_e32 v13, 0, v13, vcc
	v_cndmask_b32_e32 v14, 0, v14, vcc
	v_cndmask_b32_e32 v15, 0, v15, vcc
	v_cndmask_b32_e32 v16, 0, v16, vcc
	v_cndmask_b32_e32 v17, 0, v17, vcc
	v_cndmask_b32_e32 v18, 0, v18, vcc
	v_cndmask_b32_e32 v19, 0, v19, vcc
	v_cndmask_b32_e32 v20, 0, v20, vcc
	v_cndmask_b32_e32 v21, 0, v21, vcc
	v_cndmask_b32_e32 v22, 0, v22, vcc
	v_cndmask_b32_e32 v23, 0, v23, vcc
	v_cndmask_b32_e32 v24, 0, v24, vcc
	v_cndmask_b32_e32 v25, 0, v25, vcc
	v_cndmask_b32_e32 v26, 0, v26, vcc
	v_cndmask_b32_e32 v27, 0, v27, vcc
	v_cndmask_b32_e32 v28, 0, v28, vcc
	v_cndmask_b32_e32 v29, 0, v29, vcc
	v_cndmask_b32_e32 v30, 0, v30, vcc
	v_cndmask_b32_e32 v31, 0, v31, vcc
	s_lshl_b32 s15, s8, 4
	v_add_u32_e32 v221, s15, v236
	v_lshl_add_u32 v221, v221, 6, v237
	v_lshlrev_b32_e32 v221, 2, v221
	s_waitcnt lgkmcnt(0)
; __device__ __forceinline__ bf16x8 pack8(const float (&f)[8]) { u32x4 h; h.x = pk2(f[0], f[1]); h.y = pk2(f[2], f[3]); h.z = pk2(f[4], f[5]); h.w = pk2(f[6], f[7]); return __builtin_bit_cast(bf16x8, h); }
; template <bool FINAL> __device__ __forceinline__ void phase_s5_scan(const Fr& F) {
;     ...
;     bf16x8 Chi[4];
;     if (FINAL) {
; #pragma unroll
;         for (int ks = 0; ks < 4; ++ks) {
;             const int k = 32 * ks + 8 * lq; const float* cp = (k < 64 ? F.a->in[32] : F.a->in[33]) + (size_t)g * 1024 + l15 * 64 + (k & 63); const float sg_ = k < 64 ? 1.f : -1.f;
;             const f32x4 t0 = *(const f32x4*)cp, t1 = *(const f32x4*)(cp + 4); const float f[8] = {sg_ * t0.x, sg_ * t0.y, sg_ * t0.z, sg_ * t0.w, sg_ * t1.x, sg_ * t1.y, sg_ * t1.z, sg_ * t1.w};
;             Chi[ks] = pack8(f);
;         }
;     }
;     u32x4 ua[4]; float e0 = 0.f, e1 = 0.f;
;     {   const int ti = F.gw & 15, b = ti / 68, chunk = ti - b * 68;
; #pragma unroll
;         for (int sb = 0; sb < 4; ++sb) ua[sb] = lq < 2 ? *(const u32x4*)(U + ((size_t)b * TB + tokof(s, chunk * 64 + sb * 16 + l15)) * D + g * 16 + 8 * lq) : (u32x4){0u, 0u, 0u, 0u};
;         if (FINAL) { const float* e = E + ((size_t)(((s * 4 + b) * 64 + g) * 68 + chunk) * 64 + lane) * 2; e0 = e[0]; e1 = e[1]; } }
	global_load_dword v56, v221, s[46:47] offset:0
	global_load_dword v57, v221, s[48:49] offset:0
	global_load_dword v58, v221, s[46:47] offset:64
	global_load_dword v59, v221, s[48:49] offset:64
	global_load_dword v60, v221, s[46:47] offset:128
	global_load_dword v61, v221, s[48:49] offset:128
	global_load_dword v62, v221, s[46:47] offset:192
	global_load_dword v63, v221, s[48:49] offset:192
	global_load_dword v64, v221, s[46:47] offset:16
	global_load_dword v65, v221, s[48:49] offset:16
	global_load_dword v66, v221, s[46:47] offset:80
	global_load_dword v67, v221, s[48:49] offset:80
	global_load_dword v68, v221, s[46:47] offset:144
	global_load_dword v69, v221, s[48:49] offset:144
	global_load_dword v70, v221, s[46:47] offset:208
	global_load_dword v71, v221, s[48:49] offset:208
	global_load_dword v72, v221, s[46:47] offset:32
	global_load_dword v73, v221, s[48:49] offset:32
	global_load_dword v74, v221, s[46:47] offset:96
	global_load_dword v75, v221, s[48:49] offset:96
	global_load_dword v76, v221, s[46:47] offset:160
	global_load_dword v77, v221, s[48:49] offset:160
	global_load_dword v78, v221, s[46:47] offset:224
	global_load_dword v79, v221, s[48:49] offset:224
	global_load_dword v80, v221, s[46:47] offset:48
	global_load_dword v81, v221, s[48:49] offset:48
	global_load_dword v82, v221, s[46:47] offset:112
	global_load_dword v83, v221, s[48:49] offset:112
	global_load_dword v84, v221, s[46:47] offset:176
	global_load_dword v85, v221, s[48:49] offset:176
	global_load_dword v86, v221, s[46:47] offset:240
	global_load_dword v87, v221, s[48:49] offset:240
	s_waitcnt vmcnt(0)
	v_cvt_pk_bf16_f32 v40, v56, -v57
	v_cvt_pk_bf16_f32 v41, v58, -v59
	v_cvt_pk_bf16_f32 v42, v60, -v61
	v_cvt_pk_bf16_f32 v43, v62, -v63
	v_cvt_pk_bf16_f32 v44, v64, -v65
	v_cvt_pk_bf16_f32 v45, v66, -v67
	v_cvt_pk_bf16_f32 v46, v68, -v69
	v_cvt_pk_bf16_f32 v47, v70, -v71
	v_cvt_pk_bf16_f32 v48, v72, -v73
	v_cvt_pk_bf16_f32 v49, v74, -v75
	v_cvt_pk_bf16_f32 v50, v76, -v77
	v_cvt_pk_bf16_f32 v51, v78, -v79
	v_cvt_pk_bf16_f32 v52, v80, -v81
	v_cvt_pk_bf16_f32 v53, v82, -v83
	v_cvt_pk_bf16_f32 v54, v84, -v85
	v_cvt_pk_bf16_f32 v55, v86, -v87
	s_lshl_b32 s15, s68, 14
	v_mul_u32_u24_e32 v241, 0x400, v237
	v_lshl_add_u32 v241, v236, 4, v241
	v_add_u32_e32 v241, s15, v241
	v_mul_u32_u24_e32 v242, 0x100, v236
	v_lshl_add_u32 v242, v237, 4, v242
	v_add_u32_e32 v242, s15, v242
	s_cmp_eq_u32 s9, 0
	s_mov_b32 s18, 0xffffe000
	s_cselect_b32 s18, 0x2000, s18
	v_mov_b32_e32 v243, s18
	s_mov_b32 s14, s55
	s_lshl_b32 s15, s14, 2
	v_lshrrev_b32_e32 v244, 2, v236
	v_add_u32_e32 v244, s15, v244
	v_mul_u32_u24_e32 v245, 0xf1, v244
	v_lshrrev_b32_e32 v245, 14, v245
	v_mul_u32_u24_e32 v232, 68, v245
	v_sub_u32_e32 v244, v244, v232
	v_and_b32_e32 v232, 3, v236
	v_lshl_add_u32 v232, v244, 6, v232
	v_mov_b32_e32 v233, 0x11ff
	v_mov_b32_e32 v234, 0xff
	v_cmp_gt_u32_e32 vcc, 4, v244
	s_nop 1
	v_cndmask_b32_e32 v233, v233, v234, vcc
	v_sub_u32_e32 v233, v233, v232
	s_cmp_eq_u32 s9, 0
	s_cselect_b64 vcc, -1, 0
	s_nop 1
	v_cndmask_b32_e32 v232, v233, v232, vcc
	v_mul_u32_u24_e32 v245, 0x1100, v245
	v_add_u32_e32 v232, v232, v245
	s_lshl_b32 s16, s8, 5
	v_and_b32_e32 v233, 1, v237
	v_lshl_add_u32 v233, v233, 4, s16
	v_lshl_add_u32 v238, v232, 11, v233
	v_add_u32_e32 v244, s15, v237
	v_mul_u32_u24_e32 v245, 0xf1, v244
	v_lshrrev_b32_e32 v245, 14, v245
	v_mul_u32_u24_e32 v232, 68, v245
	v_sub_u32_e32 v244, v244, v232
	s_lshl_b32 s17, s9, 2
	v_add_u32_e32 v245, s17, v245
	v_lshl_add_u32 v245, v245, 6, s8
	v_mul_u32_u24_e32 v245, 68, v245
	v_add_u32_e32 v245, v245, v244
	v_lshl_add_u32 v245, v245, 6, v236
	v_lshlrev_b32_e32 v240, 3, v245
	global_load_dwordx2 v[246:247], v240, s[22:23] offset:0
	global_load_dwordx2 v[248:249], v240, s[22:23] offset:128
	global_load_dwordx2 v[250:251], v240, s[22:23] offset:256
	global_load_dwordx2 v[252:253], v240, s[22:23] offset:384
	global_load_dwordx4 v[56:59], v238, s[20:21]
	v_add_u32_e32 v238, v238, v243
	global_load_dwordx4 v[60:63], v238, s[20:21]
	v_add_u32_e32 v238, v238, v243
	global_load_dwordx4 v[64:67], v238, s[20:21]
	v_add_u32_e32 v238, v238, v243
	global_load_dwordx4 v[68:71], v238, s[20:21]
	v_add_u32_e32 v238, v238, v243
	global_load_dwordx4 v[72:75], v238, s[20:21]
	v_add_u32_e32 v238, v238, v243
	global_load_dwordx4 v[76:79], v238, s[20:21]
	v_add_u32_e32 v238, v238, v243
	global_load_dwordx4 v[80:83], v238, s[20:21]
	v_add_u32_e32 v238, v238, v243
	global_load_dwordx4 v[84:87], v238, s[20:21]
	v_add_u32_e32 v238, v238, v243
	global_load_dwordx4 v[88:91], v238, s[20:21]
	v_add_u32_e32 v238, v238, v243
	global_load_dwordx4 v[92:95], v238, s[20:21]
	v_add_u32_e32 v238, v238, v243
	global_load_dwordx4 v[96:99], v238, s[20:21]
	v_add_u32_e32 v238, v238, v243
	global_load_dwordx4 v[100:103], v238, s[20:21]
	v_add_u32_e32 v238, v238, v243
	global_load_dwordx4 v[104:107], v238, s[20:21]
	v_add_u32_e32 v238, v238, v243
	global_load_dwordx4 v[108:111], v238, s[20:21]
	v_add_u32_e32 v238, v238, v243
	global_load_dwordx4 v[112:115], v238, s[20:21]
	v_add_u32_e32 v238, v238, v243
	global_load_dwordx4 v[116:119], v238, s[20:21]
	v_add_u32_e32 v238, v238, v243
	s_mov_b32 s19, 0
	s_waitcnt vmcnt(0)
